# m15p + attention loops moved 24 bytes (unreachable padding) to a better instruction-fetch phase
# speedup vs baseline: 1.0131x; 1.0015x over previous
; __device__ __forceinline__ float wave_sum(float v) {
; #pragma unroll
;     for (int o = 1; o < 64; o <<= 1) v += __shfl_xor(v, o);
;     return v;
; __global__ void __launch_bounds__(512, 2) mk_fwd(Args a) {
;     ...
;                 int ll = lane; asm volatile("" : "+v"(ll));
;                 const float s1 = wave_sum(a.in[10][ll] * a.in[11][ll]), s2 = wave_sum(a.in[12][ll] * a.in[13][ll]);
;                 const float lam = __expf(s1) - __expf(s2) + 0.2f;
.LBB0_494:
	v_readlane_b32 s4, v254, 33
	v_readlane_b32 s5, v254, 34
	s_andn2_b64 vcc, exec, s[4:5]
	s_cbranch_vccnz .LBB0_611
	s_load_dwordx8 s[12:19], s[0:1], 0x50
	v_mov_b32_e32 v144, v203
	v_xor_b32_e32 v6, 2, v211
	v_ashrrev_i32_e32 v145, 31, v144
	s_waitcnt lgkmcnt(0)
	v_lshlrev_b64 v[0:1], 2, v[144:145]
	v_lshl_add_u64 v[2:3], s[12:13], 0, v[0:1]
	global_load_dword v4, v[2:3], off
	v_lshl_add_u64 v[2:3], s[14:15], 0, v[0:1]
	global_load_dword v5, v[2:3], off
	v_lshl_add_u64 v[2:3], s[16:17], 0, v[0:1]
	v_lshl_add_u64 v[0:1], s[18:19], 0, v[0:1]
	global_load_dword v2, v[2:3], off
	v_xor_b32_e32 v3, 1, v211
	global_load_dword v0, v[0:1], off
	v_and_b32_e32 v1, 64, v211
	v_add_u32_e32 v1, 64, v1
	v_cmp_lt_i32_e32 vcc, v3, v1
	v_xor_b32_e32 v7, 4, v211
	v_xor_b32_e32 v8, 8, v211
	v_cndmask_b32_e32 v3, v211, v3, vcc
	v_lshlrev_b32_e32 v3, 2, v3
	v_cmp_lt_i32_e32 vcc, v6, v1
	v_xor_b32_e32 v9, 16, v211
	v_xor_b32_e32 v10, 32, v211
	v_cndmask_b32_e32 v6, v211, v6, vcc
	v_lshlrev_b32_e32 v6, 2, v6
	v_cmp_lt_i32_e32 vcc, v7, v1
	s_mov_b32 s4, 0
	s_waitcnt vmcnt(2)
	v_mul_f32_e32 v11, v4, v5
	ds_bpermute_b32 v11, v3, v11
	s_waitcnt vmcnt(0)
	v_mul_f32_e32 v12, v2, v0
	ds_bpermute_b32 v3, v3, v12
	s_waitcnt lgkmcnt(1)
	v_fmac_f32_e32 v11, v4, v5
	v_cndmask_b32_e32 v4, v211, v7, vcc
	v_lshlrev_b32_e32 v4, 2, v4
	v_cmp_lt_i32_e32 vcc, v8, v1
	s_waitcnt lgkmcnt(0)
	v_fmac_f32_e32 v3, v2, v0
	ds_bpermute_b32 v0, v6, v11
	ds_bpermute_b32 v2, v6, v3
	v_cndmask_b32_e32 v5, v211, v8, vcc
	v_lshlrev_b32_e32 v5, 2, v5
	v_cmp_lt_i32_e32 vcc, v9, v1
	s_waitcnt lgkmcnt(1)
	v_add_f32_e32 v0, v11, v0
	s_waitcnt lgkmcnt(0)
	v_add_f32_e32 v2, v3, v2
	ds_bpermute_b32 v3, v4, v0
	ds_bpermute_b32 v4, v4, v2
	s_waitcnt lgkmcnt(1)
	v_add_f32_e32 v0, v0, v3
	s_waitcnt lgkmcnt(0)
	v_add_f32_e32 v2, v2, v4
	ds_bpermute_b32 v3, v5, v0
	ds_bpermute_b32 v4, v5, v2
	v_cndmask_b32_e32 v5, v211, v9, vcc
	v_lshlrev_b32_e32 v5, 2, v5
	v_cmp_lt_i32_e32 vcc, v10, v1
	s_waitcnt lgkmcnt(1)
	v_add_f32_e32 v0, v0, v3
	s_waitcnt lgkmcnt(0)
	v_add_f32_e32 v2, v2, v4
	ds_bpermute_b32 v3, v5, v0
	ds_bpermute_b32 v4, v5, v2
	v_cndmask_b32_e32 v1, v211, v10, vcc
	v_lshlrev_b32_e32 v145, 2, v1
	s_waitcnt lgkmcnt(1)
	v_add_f32_e32 v0, v0, v3
	s_waitcnt lgkmcnt(0)
	v_add_f32_e32 v1, v2, v4
	ds_bpermute_b32 v2, v145, v0
	ds_bpermute_b32 v3, v145, v1
	s_waitcnt lgkmcnt(1)
	v_add_f32_e32 v0, v0, v2
	s_waitcnt lgkmcnt(0)
	v_add_f32_e32 v1, v1, v3
	v_mul_f32_e32 v0, 0x3fb8aa3b, v0
	v_mul_f32_e32 v1, 0x3fb8aa3b, v1
	v_exp_f32_e32 v0, v0
	v_exp_f32_e32 v1, v1
	s_nop 0
	v_sub_f32_e32 v0, v0, v1
	v_add_f32_e32 v154, 0x3e4ccccd, v0
	s_branch .LBB0_497
	s_nop 0
	s_nop 0
	s_nop 0
	s_nop 0
	s_nop 0
	s_nop 0
